# P0 dt reduce-scatter: 30 exchange steps done with DPP adds instead of ds_bpermute round trips
# baseline (speedup 1.0000x reference)
.LBB0_38:
	s_add_i32 s25, s16, s78
	s_cmp_lt_i32 s25, 0xc000
	s_cselect_b32 s14, s25, s16
	s_add_i32 s10, s16, 0xffff8000
	s_ashr_i32 s17, s16, 31
	s_cmp_lt_i32 s16, 0x8000
	v_readlane_b32 s36, v253, 0
	s_cselect_b32 s11, s17, 0
	s_cselect_b32 s10, s16, s10
	v_readlane_b32 s37, v253, 1
	v_readlane_b32 s38, v253, 2
	v_readlane_b32 s39, v253, 3
	s_cselect_b32 s15, s37, s39
	s_cselect_b32 s18, s36, s38
	s_lshl_b64 s[10:11], s[10:11], 12
	s_add_u32 s10, s18, s10
	s_addc_u32 s11, s15, s11
	s_waitcnt lgkmcnt(0)
	s_add_i32 s10, s14, 0xffff8000
	s_ashr_i32 s15, s14, 31
	s_cmp_lt_i32 s14, 0x8000
	s_cselect_b32 s11, s15, 0
	s_cselect_b32 s10, s14, s10
	s_cselect_b32 s18, s37, s39
	s_cselect_b32 s19, s36, s38
	s_lshl_b64 s[10:11], s[10:11], 12
	s_add_u32 s10, s19, s10
	s_addc_u32 s11, s18, s11
	s_lshl_b64 s[10:11], s[16:17], 11
	s_lshl_b64 s[18:19], s[14:15], 11
	v_lshl_add_u64 v[34:35], v[40:41], 0, s[10:11]
	v_lshl_add_u64 v[36:37], v[40:41], 0, s[18:19]
	v_readlane_b32 s40, v253, 4
	v_readlane_b32 s41, v253, 5
	v_readlane_b32 s42, v253, 6
	v_readlane_b32 s43, v253, 7
	v_readlane_b32 s44, v253, 8
	v_readlane_b32 s45, v253, 9
	v_readlane_b32 s46, v253, 10
	v_readlane_b32 s47, v253, 11
	v_readlane_b32 s48, v253, 12
	v_readlane_b32 s49, v253, 13
	v_readlane_b32 s50, v253, 14
	v_readlane_b32 s51, v253, 15
	s_waitcnt vmcnt(2)
	v_mov_b64_e32 v[10:11], v[176:177]
	v_mov_b64_e32 v[12:13], v[178:179]
	v_mov_b64_e32 v[2:3], v[180:181]
	v_mov_b64_e32 v[4:5], v[182:183]
	v_mov_b64_e32 v[14:15], v[184:185]
	v_mov_b64_e32 v[16:17], v[186:187]
	v_mov_b64_e32 v[6:7], v[188:189]
	v_mov_b64_e32 v[8:9], v[190:191]
	v_cvt_pk_bf16_f32 v56, v26, v27
	v_cvt_pk_bf16_f32 v57, v28, v29
	s_waitcnt vmcnt(6)
	v_cvt_pk_bf16_f32 v58, v22, v23
	v_cvt_pk_bf16_f32 v59, v24, v25
	s_waitcnt vmcnt(5)
	v_cvt_pk_bf16_f32 v60, v10, v11
	v_cvt_pk_bf16_f32 v61, v12, v13
	s_waitcnt vmcnt(4)
	v_cvt_pk_bf16_f32 v62, v2, v3
	v_cvt_pk_bf16_f32 v63, v4, v5
	global_store_dwordx2 v[34:35], v[56:57], off
	global_store_dwordx2 v[34:35], v[58:59], off offset:512
	global_store_dwordx2 v[34:35], v[60:61], off offset:1024
	global_store_dwordx2 v[34:35], v[62:63], off offset:1536
	s_waitcnt vmcnt(7)
	v_cvt_pk_bf16_f32 v34, v30, v31
	v_cvt_pk_bf16_f32 v35, v32, v33
	s_waitcnt vmcnt(6)
	v_cvt_pk_bf16_f32 v56, v18, v19
	v_cvt_pk_bf16_f32 v57, v20, v21
	s_waitcnt vmcnt(5)
	v_cvt_pk_bf16_f32 v58, v14, v15
	v_cvt_pk_bf16_f32 v59, v16, v17
	s_waitcnt vmcnt(4)
	v_cvt_pk_bf16_f32 v60, v6, v7
	v_cvt_pk_bf16_f32 v61, v8, v9
	global_store_dwordx2 v[36:37], v[34:35], off
	global_store_dwordx2 v[36:37], v[56:57], off offset:512
	global_store_dwordx2 v[36:37], v[58:59], off offset:1024
	global_store_dwordx2 v[36:37], v[60:61], off offset:1536
	ds_read_b128 v[176:179], v44 offset:0
	ds_read_b128 v[180:183], v44 offset:1024
	ds_read_b128 v[184:187], v44 offset:2048
	ds_read_b128 v[188:191], v44 offset:3072
	ds_read_b128 v[192:195], v44 offset:4096
	ds_read_b128 v[196:199], v44 offset:5120
	ds_read_b128 v[200:203], v44 offset:6144
	ds_read_b128 v[204:207], v44 offset:7168
	s_waitcnt lgkmcnt(4)
	v_pk_mul_f32 v[208:209], v[26:27], v[176:177]
	v_pk_mul_f32 v[210:211], v[30:31], v[176:177]
	v_pk_fma_f32 v[208:209], v[28:29], v[178:179], v[208:209]
	v_pk_fma_f32 v[210:211], v[32:33], v[178:179], v[210:211]
	v_pk_fma_f32 v[208:209], v[22:23], v[180:181], v[208:209]
	v_pk_fma_f32 v[210:211], v[18:19], v[180:181], v[210:211]
	v_pk_fma_f32 v[208:209], v[24:25], v[182:183], v[208:209]
	v_pk_fma_f32 v[210:211], v[20:21], v[182:183], v[210:211]
	v_pk_fma_f32 v[208:209], v[10:11], v[184:185], v[208:209]
	v_pk_fma_f32 v[210:211], v[14:15], v[184:185], v[210:211]
	v_pk_fma_f32 v[208:209], v[12:13], v[186:187], v[208:209]
	v_pk_fma_f32 v[210:211], v[16:17], v[186:187], v[210:211]
	v_pk_fma_f32 v[208:209], v[2:3], v[188:189], v[208:209]
	v_pk_fma_f32 v[210:211], v[6:7], v[188:189], v[210:211]
	v_pk_fma_f32 v[208:209], v[4:5], v[190:191], v[208:209]
	v_pk_fma_f32 v[210:211], v[8:9], v[190:191], v[210:211]
	v_add_f32_e32 v142, v208, v209
	v_add_f32_e32 v143, v210, v211
	ds_read_b128 v[176:179], v44 offset:8192
	ds_read_b128 v[180:183], v44 offset:9216
	ds_read_b128 v[184:187], v44 offset:10240
	ds_read_b128 v[188:191], v44 offset:11264
	s_waitcnt lgkmcnt(4)
	v_pk_mul_f32 v[208:209], v[26:27], v[192:193]
	v_pk_mul_f32 v[210:211], v[30:31], v[192:193]
	v_pk_fma_f32 v[208:209], v[28:29], v[194:195], v[208:209]
	v_pk_fma_f32 v[210:211], v[32:33], v[194:195], v[210:211]
	v_pk_fma_f32 v[208:209], v[22:23], v[196:197], v[208:209]
	v_pk_fma_f32 v[210:211], v[18:19], v[196:197], v[210:211]
	v_pk_fma_f32 v[208:209], v[24:25], v[198:199], v[208:209]
	v_pk_fma_f32 v[210:211], v[20:21], v[198:199], v[210:211]
	v_pk_fma_f32 v[208:209], v[10:11], v[200:201], v[208:209]
	v_pk_fma_f32 v[210:211], v[14:15], v[200:201], v[210:211]
	v_pk_fma_f32 v[208:209], v[12:13], v[202:203], v[208:209]
	v_pk_fma_f32 v[210:211], v[16:17], v[202:203], v[210:211]
	v_pk_fma_f32 v[208:209], v[2:3], v[204:205], v[208:209]
	v_pk_fma_f32 v[210:211], v[6:7], v[204:205], v[210:211]
	v_pk_fma_f32 v[208:209], v[4:5], v[206:207], v[208:209]
	v_pk_fma_f32 v[210:211], v[8:9], v[206:207], v[210:211]
	v_add_f32_e32 v144, v208, v209
	v_add_f32_e32 v145, v210, v211
	ds_read_b128 v[192:195], v44 offset:12288
	ds_read_b128 v[196:199], v44 offset:13312
	ds_read_b128 v[200:203], v44 offset:14336
	ds_read_b128 v[204:207], v44 offset:15360
	s_waitcnt lgkmcnt(4)
	v_pk_mul_f32 v[208:209], v[26:27], v[176:177]
	v_pk_mul_f32 v[210:211], v[30:31], v[176:177]
	v_pk_fma_f32 v[208:209], v[28:29], v[178:179], v[208:209]
	v_pk_fma_f32 v[210:211], v[32:33], v[178:179], v[210:211]
	v_pk_fma_f32 v[208:209], v[22:23], v[180:181], v[208:209]
	v_pk_fma_f32 v[210:211], v[18:19], v[180:181], v[210:211]
	v_pk_fma_f32 v[208:209], v[24:25], v[182:183], v[208:209]
	v_pk_fma_f32 v[210:211], v[20:21], v[182:183], v[210:211]
	v_pk_fma_f32 v[208:209], v[10:11], v[184:185], v[208:209]
	v_pk_fma_f32 v[210:211], v[14:15], v[184:185], v[210:211]
	v_pk_fma_f32 v[208:209], v[12:13], v[186:187], v[208:209]
	v_pk_fma_f32 v[210:211], v[16:17], v[186:187], v[210:211]
	v_pk_fma_f32 v[208:209], v[2:3], v[188:189], v[208:209]
	v_pk_fma_f32 v[210:211], v[6:7], v[188:189], v[210:211]
	v_pk_fma_f32 v[208:209], v[4:5], v[190:191], v[208:209]
	v_pk_fma_f32 v[210:211], v[8:9], v[190:191], v[210:211]
	v_add_f32_e32 v146, v208, v209
	v_add_f32_e32 v147, v210, v211
	ds_read_b128 v[176:179], v44 offset:16384
	ds_read_b128 v[180:183], v44 offset:17408
	ds_read_b128 v[184:187], v44 offset:18432
	ds_read_b128 v[188:191], v44 offset:19456
	s_waitcnt lgkmcnt(4)
	v_pk_mul_f32 v[208:209], v[26:27], v[192:193]
	v_pk_mul_f32 v[210:211], v[30:31], v[192:193]
	v_pk_fma_f32 v[208:209], v[28:29], v[194:195], v[208:209]
	v_pk_fma_f32 v[210:211], v[32:33], v[194:195], v[210:211]
	v_pk_fma_f32 v[208:209], v[22:23], v[196:197], v[208:209]
	v_pk_fma_f32 v[210:211], v[18:19], v[196:197], v[210:211]
	v_pk_fma_f32 v[208:209], v[24:25], v[198:199], v[208:209]
	v_pk_fma_f32 v[210:211], v[20:21], v[198:199], v[210:211]
	v_pk_fma_f32 v[208:209], v[10:11], v[200:201], v[208:209]
	v_pk_fma_f32 v[210:211], v[14:15], v[200:201], v[210:211]
	v_pk_fma_f32 v[208:209], v[12:13], v[202:203], v[208:209]
	v_pk_fma_f32 v[210:211], v[16:17], v[202:203], v[210:211]
	v_pk_fma_f32 v[208:209], v[2:3], v[204:205], v[208:209]
	v_pk_fma_f32 v[210:211], v[6:7], v[204:205], v[210:211]
	v_pk_fma_f32 v[208:209], v[4:5], v[206:207], v[208:209]
	v_pk_fma_f32 v[210:211], v[8:9], v[206:207], v[210:211]
	v_add_f32_e32 v148, v208, v209
	v_add_f32_e32 v149, v210, v211
	ds_read_b128 v[192:195], v44 offset:20480
	ds_read_b128 v[196:199], v44 offset:21504
	ds_read_b128 v[200:203], v44 offset:22528
	ds_read_b128 v[204:207], v44 offset:23552
	s_waitcnt lgkmcnt(4)
	v_pk_mul_f32 v[208:209], v[26:27], v[176:177]
	v_pk_mul_f32 v[210:211], v[30:31], v[176:177]
	v_pk_fma_f32 v[208:209], v[28:29], v[178:179], v[208:209]
	v_pk_fma_f32 v[210:211], v[32:33], v[178:179], v[210:211]
	v_pk_fma_f32 v[208:209], v[22:23], v[180:181], v[208:209]
	v_pk_fma_f32 v[210:211], v[18:19], v[180:181], v[210:211]
	v_pk_fma_f32 v[208:209], v[24:25], v[182:183], v[208:209]
	v_pk_fma_f32 v[210:211], v[20:21], v[182:183], v[210:211]
	v_pk_fma_f32 v[208:209], v[10:11], v[184:185], v[208:209]
	v_pk_fma_f32 v[210:211], v[14:15], v[184:185], v[210:211]
	v_pk_fma_f32 v[208:209], v[12:13], v[186:187], v[208:209]
	v_pk_fma_f32 v[210:211], v[16:17], v[186:187], v[210:211]
	v_pk_fma_f32 v[208:209], v[2:3], v[188:189], v[208:209]
	v_pk_fma_f32 v[210:211], v[6:7], v[188:189], v[210:211]
	v_pk_fma_f32 v[208:209], v[4:5], v[190:191], v[208:209]
	v_pk_fma_f32 v[210:211], v[8:9], v[190:191], v[210:211]
	v_add_f32_e32 v150, v208, v209
	v_add_f32_e32 v151, v210, v211
	ds_read_b128 v[176:179], v44 offset:24576
	ds_read_b128 v[180:183], v44 offset:25600
	ds_read_b128 v[184:187], v44 offset:26624
	ds_read_b128 v[188:191], v44 offset:27648
	s_waitcnt lgkmcnt(4)
	v_pk_mul_f32 v[208:209], v[26:27], v[192:193]
	v_pk_mul_f32 v[210:211], v[30:31], v[192:193]
	v_pk_fma_f32 v[208:209], v[28:29], v[194:195], v[208:209]
	v_pk_fma_f32 v[210:211], v[32:33], v[194:195], v[210:211]
	v_pk_fma_f32 v[208:209], v[22:23], v[196:197], v[208:209]
	v_pk_fma_f32 v[210:211], v[18:19], v[196:197], v[210:211]
	v_pk_fma_f32 v[208:209], v[24:25], v[198:199], v[208:209]
	v_pk_fma_f32 v[210:211], v[20:21], v[198:199], v[210:211]
	v_pk_fma_f32 v[208:209], v[10:11], v[200:201], v[208:209]
	v_pk_fma_f32 v[210:211], v[14:15], v[200:201], v[210:211]
	v_pk_fma_f32 v[208:209], v[12:13], v[202:203], v[208:209]
	v_pk_fma_f32 v[210:211], v[16:17], v[202:203], v[210:211]
	v_pk_fma_f32 v[208:209], v[2:3], v[204:205], v[208:209]
	v_pk_fma_f32 v[210:211], v[6:7], v[204:205], v[210:211]
	v_pk_fma_f32 v[208:209], v[4:5], v[206:207], v[208:209]
	v_pk_fma_f32 v[210:211], v[8:9], v[206:207], v[210:211]
	v_add_f32_e32 v152, v208, v209
	v_add_f32_e32 v153, v210, v211
	ds_read_b128 v[192:195], v44 offset:28672
	ds_read_b128 v[196:199], v44 offset:29696
	ds_read_b128 v[200:203], v44 offset:30720
	ds_read_b128 v[204:207], v44 offset:31744
	s_waitcnt lgkmcnt(4)
	v_pk_mul_f32 v[208:209], v[26:27], v[176:177]
	v_pk_mul_f32 v[210:211], v[30:31], v[176:177]
	v_pk_fma_f32 v[208:209], v[28:29], v[178:179], v[208:209]
	v_pk_fma_f32 v[210:211], v[32:33], v[178:179], v[210:211]
	v_pk_fma_f32 v[208:209], v[22:23], v[180:181], v[208:209]
	v_pk_fma_f32 v[210:211], v[18:19], v[180:181], v[210:211]
	v_pk_fma_f32 v[208:209], v[24:25], v[182:183], v[208:209]
	v_pk_fma_f32 v[210:211], v[20:21], v[182:183], v[210:211]
	v_pk_fma_f32 v[208:209], v[10:11], v[184:185], v[208:209]
	v_pk_fma_f32 v[210:211], v[14:15], v[184:185], v[210:211]
	v_pk_fma_f32 v[208:209], v[12:13], v[186:187], v[208:209]
	v_pk_fma_f32 v[210:211], v[16:17], v[186:187], v[210:211]
	v_pk_fma_f32 v[208:209], v[2:3], v[188:189], v[208:209]
	v_pk_fma_f32 v[210:211], v[6:7], v[188:189], v[210:211]
	v_pk_fma_f32 v[208:209], v[4:5], v[190:191], v[208:209]
	v_pk_fma_f32 v[210:211], v[8:9], v[190:191], v[210:211]
	v_add_f32_e32 v154, v208, v209
	v_add_f32_e32 v155, v210, v211
	ds_read_b128 v[176:179], v44 offset:32768
	ds_read_b128 v[180:183], v44 offset:33792
	ds_read_b128 v[184:187], v44 offset:34816
	ds_read_b128 v[188:191], v44 offset:35840
	s_waitcnt lgkmcnt(4)
	v_pk_mul_f32 v[208:209], v[26:27], v[192:193]
	v_pk_mul_f32 v[210:211], v[30:31], v[192:193]
	v_pk_fma_f32 v[208:209], v[28:29], v[194:195], v[208:209]
	v_pk_fma_f32 v[210:211], v[32:33], v[194:195], v[210:211]
	v_pk_fma_f32 v[208:209], v[22:23], v[196:197], v[208:209]
	v_pk_fma_f32 v[210:211], v[18:19], v[196:197], v[210:211]
	v_pk_fma_f32 v[208:209], v[24:25], v[198:199], v[208:209]
	v_pk_fma_f32 v[210:211], v[20:21], v[198:199], v[210:211]
	v_pk_fma_f32 v[208:209], v[10:11], v[200:201], v[208:209]
	v_pk_fma_f32 v[210:211], v[14:15], v[200:201], v[210:211]
	v_pk_fma_f32 v[208:209], v[12:13], v[202:203], v[208:209]
	v_pk_fma_f32 v[210:211], v[16:17], v[202:203], v[210:211]
	v_pk_fma_f32 v[208:209], v[2:3], v[204:205], v[208:209]
	v_pk_fma_f32 v[210:211], v[6:7], v[204:205], v[210:211]
	v_pk_fma_f32 v[208:209], v[4:5], v[206:207], v[208:209]
	v_pk_fma_f32 v[210:211], v[8:9], v[206:207], v[210:211]
	v_add_f32_e32 v156, v208, v209
	v_add_f32_e32 v157, v210, v211
	ds_read_b128 v[192:195], v44 offset:36864
	ds_read_b128 v[196:199], v44 offset:37888
	ds_read_b128 v[200:203], v44 offset:38912
	ds_read_b128 v[204:207], v44 offset:39936
	s_waitcnt lgkmcnt(4)
	v_pk_mul_f32 v[208:209], v[26:27], v[176:177]
	v_pk_mul_f32 v[210:211], v[30:31], v[176:177]
	v_pk_fma_f32 v[208:209], v[28:29], v[178:179], v[208:209]
	v_pk_fma_f32 v[210:211], v[32:33], v[178:179], v[210:211]
	v_pk_fma_f32 v[208:209], v[22:23], v[180:181], v[208:209]
	v_pk_fma_f32 v[210:211], v[18:19], v[180:181], v[210:211]
	v_pk_fma_f32 v[208:209], v[24:25], v[182:183], v[208:209]
	v_pk_fma_f32 v[210:211], v[20:21], v[182:183], v[210:211]
	v_pk_fma_f32 v[208:209], v[10:11], v[184:185], v[208:209]
	v_pk_fma_f32 v[210:211], v[14:15], v[184:185], v[210:211]
	v_pk_fma_f32 v[208:209], v[12:13], v[186:187], v[208:209]
	v_pk_fma_f32 v[210:211], v[16:17], v[186:187], v[210:211]
	v_pk_fma_f32 v[208:209], v[2:3], v[188:189], v[208:209]
	v_pk_fma_f32 v[210:211], v[6:7], v[188:189], v[210:211]
	v_pk_fma_f32 v[208:209], v[4:5], v[190:191], v[208:209]
	v_pk_fma_f32 v[210:211], v[8:9], v[190:191], v[210:211]
	v_add_f32_e32 v158, v208, v209
	v_add_f32_e32 v159, v210, v211
	ds_read_b128 v[176:179], v44 offset:40960
	ds_read_b128 v[180:183], v44 offset:41984
	ds_read_b128 v[184:187], v44 offset:43008
	ds_read_b128 v[188:191], v44 offset:44032
	s_waitcnt lgkmcnt(4)
	v_pk_mul_f32 v[208:209], v[26:27], v[192:193]
	v_pk_mul_f32 v[210:211], v[30:31], v[192:193]
	v_pk_fma_f32 v[208:209], v[28:29], v[194:195], v[208:209]
	v_pk_fma_f32 v[210:211], v[32:33], v[194:195], v[210:211]
	v_pk_fma_f32 v[208:209], v[22:23], v[196:197], v[208:209]
	v_pk_fma_f32 v[210:211], v[18:19], v[196:197], v[210:211]
	v_pk_fma_f32 v[208:209], v[24:25], v[198:199], v[208:209]
	v_pk_fma_f32 v[210:211], v[20:21], v[198:199], v[210:211]
	v_pk_fma_f32 v[208:209], v[10:11], v[200:201], v[208:209]
	v_pk_fma_f32 v[210:211], v[14:15], v[200:201], v[210:211]
	v_pk_fma_f32 v[208:209], v[12:13], v[202:203], v[208:209]
	v_pk_fma_f32 v[210:211], v[16:17], v[202:203], v[210:211]
	v_pk_fma_f32 v[208:209], v[2:3], v[204:205], v[208:209]
	v_pk_fma_f32 v[210:211], v[6:7], v[204:205], v[210:211]
	v_pk_fma_f32 v[208:209], v[4:5], v[206:207], v[208:209]
	v_pk_fma_f32 v[210:211], v[8:9], v[206:207], v[210:211]
	v_add_f32_e32 v160, v208, v209
	v_add_f32_e32 v161, v210, v211
	ds_read_b128 v[192:195], v44 offset:45056
	ds_read_b128 v[196:199], v44 offset:46080
	ds_read_b128 v[200:203], v44 offset:47104
	ds_read_b128 v[204:207], v44 offset:48128
	s_waitcnt lgkmcnt(4)
	v_pk_mul_f32 v[208:209], v[26:27], v[176:177]
	v_pk_mul_f32 v[210:211], v[30:31], v[176:177]
	v_pk_fma_f32 v[208:209], v[28:29], v[178:179], v[208:209]
	v_pk_fma_f32 v[210:211], v[32:33], v[178:179], v[210:211]
	v_pk_fma_f32 v[208:209], v[22:23], v[180:181], v[208:209]
	v_pk_fma_f32 v[210:211], v[18:19], v[180:181], v[210:211]
	v_pk_fma_f32 v[208:209], v[24:25], v[182:183], v[208:209]
	v_pk_fma_f32 v[210:211], v[20:21], v[182:183], v[210:211]
	v_pk_fma_f32 v[208:209], v[10:11], v[184:185], v[208:209]
	v_pk_fma_f32 v[210:211], v[14:15], v[184:185], v[210:211]
	v_pk_fma_f32 v[208:209], v[12:13], v[186:187], v[208:209]
	v_pk_fma_f32 v[210:211], v[16:17], v[186:187], v[210:211]
	v_pk_fma_f32 v[208:209], v[2:3], v[188:189], v[208:209]
	v_pk_fma_f32 v[210:211], v[6:7], v[188:189], v[210:211]
	v_pk_fma_f32 v[208:209], v[4:5], v[190:191], v[208:209]
	v_pk_fma_f32 v[210:211], v[8:9], v[190:191], v[210:211]
	v_add_f32_e32 v162, v208, v209
	v_add_f32_e32 v163, v210, v211
	ds_read_b128 v[176:179], v44 offset:49152
	ds_read_b128 v[180:183], v44 offset:50176
	ds_read_b128 v[184:187], v44 offset:51200
	ds_read_b128 v[188:191], v44 offset:52224
	s_waitcnt lgkmcnt(4)
	v_pk_mul_f32 v[208:209], v[26:27], v[192:193]
	v_pk_mul_f32 v[210:211], v[30:31], v[192:193]
	v_pk_fma_f32 v[208:209], v[28:29], v[194:195], v[208:209]
	v_pk_fma_f32 v[210:211], v[32:33], v[194:195], v[210:211]
	v_pk_fma_f32 v[208:209], v[22:23], v[196:197], v[208:209]
	v_pk_fma_f32 v[210:211], v[18:19], v[196:197], v[210:211]
	v_pk_fma_f32 v[208:209], v[24:25], v[198:199], v[208:209]
	v_pk_fma_f32 v[210:211], v[20:21], v[198:199], v[210:211]
	v_pk_fma_f32 v[208:209], v[10:11], v[200:201], v[208:209]
	v_pk_fma_f32 v[210:211], v[14:15], v[200:201], v[210:211]
	v_pk_fma_f32 v[208:209], v[12:13], v[202:203], v[208:209]
	v_pk_fma_f32 v[210:211], v[16:17], v[202:203], v[210:211]
	v_pk_fma_f32 v[208:209], v[2:3], v[204:205], v[208:209]
	v_pk_fma_f32 v[210:211], v[6:7], v[204:205], v[210:211]
	v_pk_fma_f32 v[208:209], v[4:5], v[206:207], v[208:209]
	v_pk_fma_f32 v[210:211], v[8:9], v[206:207], v[210:211]
	v_add_f32_e32 v164, v208, v209
	v_add_f32_e32 v165, v210, v211
	ds_read_b128 v[192:195], v44 offset:53248
	ds_read_b128 v[196:199], v44 offset:54272
	ds_read_b128 v[200:203], v44 offset:55296
	ds_read_b128 v[204:207], v44 offset:56320
	s_waitcnt lgkmcnt(4)
	v_pk_mul_f32 v[208:209], v[26:27], v[176:177]
	v_pk_mul_f32 v[210:211], v[30:31], v[176:177]
	v_pk_fma_f32 v[208:209], v[28:29], v[178:179], v[208:209]
	v_pk_fma_f32 v[210:211], v[32:33], v[178:179], v[210:211]
	v_pk_fma_f32 v[208:209], v[22:23], v[180:181], v[208:209]
	v_pk_fma_f32 v[210:211], v[18:19], v[180:181], v[210:211]
	v_pk_fma_f32 v[208:209], v[24:25], v[182:183], v[208:209]
	v_pk_fma_f32 v[210:211], v[20:21], v[182:183], v[210:211]
	v_pk_fma_f32 v[208:209], v[10:11], v[184:185], v[208:209]
	v_pk_fma_f32 v[210:211], v[14:15], v[184:185], v[210:211]
	v_pk_fma_f32 v[208:209], v[12:13], v[186:187], v[208:209]
	v_pk_fma_f32 v[210:211], v[16:17], v[186:187], v[210:211]
	v_pk_fma_f32 v[208:209], v[2:3], v[188:189], v[208:209]
	v_pk_fma_f32 v[210:211], v[6:7], v[188:189], v[210:211]
	v_pk_fma_f32 v[208:209], v[4:5], v[190:191], v[208:209]
	v_pk_fma_f32 v[210:211], v[8:9], v[190:191], v[210:211]
	v_add_f32_e32 v166, v208, v209
	v_add_f32_e32 v167, v210, v211
	ds_read_b128 v[176:179], v44 offset:57344
	ds_read_b128 v[180:183], v44 offset:58368
	ds_read_b128 v[184:187], v44 offset:59392
	ds_read_b128 v[188:191], v44 offset:60416
	s_waitcnt lgkmcnt(4)
	v_pk_mul_f32 v[208:209], v[26:27], v[192:193]
	v_pk_mul_f32 v[210:211], v[30:31], v[192:193]
	v_pk_fma_f32 v[208:209], v[28:29], v[194:195], v[208:209]
	v_pk_fma_f32 v[210:211], v[32:33], v[194:195], v[210:211]
	v_pk_fma_f32 v[208:209], v[22:23], v[196:197], v[208:209]
	v_pk_fma_f32 v[210:211], v[18:19], v[196:197], v[210:211]
	v_pk_fma_f32 v[208:209], v[24:25], v[198:199], v[208:209]
	v_pk_fma_f32 v[210:211], v[20:21], v[198:199], v[210:211]
	v_pk_fma_f32 v[208:209], v[10:11], v[200:201], v[208:209]
	v_pk_fma_f32 v[210:211], v[14:15], v[200:201], v[210:211]
	v_pk_fma_f32 v[208:209], v[12:13], v[202:203], v[208:209]
	v_pk_fma_f32 v[210:211], v[16:17], v[202:203], v[210:211]
	v_pk_fma_f32 v[208:209], v[2:3], v[204:205], v[208:209]
	v_pk_fma_f32 v[210:211], v[6:7], v[204:205], v[210:211]
	v_pk_fma_f32 v[208:209], v[4:5], v[206:207], v[208:209]
	v_pk_fma_f32 v[210:211], v[8:9], v[206:207], v[210:211]
	v_add_f32_e32 v168, v208, v209
	v_add_f32_e32 v169, v210, v211
	ds_read_b128 v[192:195], v44 offset:61440
	ds_read_b128 v[196:199], v44 offset:62464
	ds_read_b128 v[200:203], v44 offset:63488
	ds_read_b128 v[204:207], v44 offset:64512
	s_waitcnt lgkmcnt(4)
	v_pk_mul_f32 v[208:209], v[26:27], v[176:177]
	v_pk_mul_f32 v[210:211], v[30:31], v[176:177]
	v_pk_fma_f32 v[208:209], v[28:29], v[178:179], v[208:209]
	v_pk_fma_f32 v[210:211], v[32:33], v[178:179], v[210:211]
	v_pk_fma_f32 v[208:209], v[22:23], v[180:181], v[208:209]
	v_pk_fma_f32 v[210:211], v[18:19], v[180:181], v[210:211]
	v_pk_fma_f32 v[208:209], v[24:25], v[182:183], v[208:209]
	v_pk_fma_f32 v[210:211], v[20:21], v[182:183], v[210:211]
	v_pk_fma_f32 v[208:209], v[10:11], v[184:185], v[208:209]
	v_pk_fma_f32 v[210:211], v[14:15], v[184:185], v[210:211]
	v_pk_fma_f32 v[208:209], v[12:13], v[186:187], v[208:209]
	v_pk_fma_f32 v[210:211], v[16:17], v[186:187], v[210:211]
	v_pk_fma_f32 v[208:209], v[2:3], v[188:189], v[208:209]
	v_pk_fma_f32 v[210:211], v[6:7], v[188:189], v[210:211]
	v_pk_fma_f32 v[208:209], v[4:5], v[190:191], v[208:209]
	v_pk_fma_f32 v[210:211], v[8:9], v[190:191], v[210:211]
	v_add_f32_e32 v170, v208, v209
	v_add_f32_e32 v171, v210, v211
	s_waitcnt lgkmcnt(0)
	v_pk_mul_f32 v[208:209], v[26:27], v[192:193]
	v_pk_mul_f32 v[210:211], v[30:31], v[192:193]
	v_pk_fma_f32 v[208:209], v[28:29], v[194:195], v[208:209]
	v_pk_fma_f32 v[210:211], v[32:33], v[194:195], v[210:211]
	v_pk_fma_f32 v[208:209], v[22:23], v[196:197], v[208:209]
	v_pk_fma_f32 v[210:211], v[18:19], v[196:197], v[210:211]
	v_pk_fma_f32 v[208:209], v[24:25], v[198:199], v[208:209]
	v_pk_fma_f32 v[210:211], v[20:21], v[198:199], v[210:211]
	v_pk_fma_f32 v[208:209], v[10:11], v[200:201], v[208:209]
	v_pk_fma_f32 v[210:211], v[14:15], v[200:201], v[210:211]
	v_pk_fma_f32 v[208:209], v[12:13], v[202:203], v[208:209]
	v_pk_fma_f32 v[210:211], v[16:17], v[202:203], v[210:211]
	v_pk_fma_f32 v[208:209], v[2:3], v[204:205], v[208:209]
	v_pk_fma_f32 v[210:211], v[6:7], v[204:205], v[210:211]
	v_pk_fma_f32 v[208:209], v[4:5], v[206:207], v[208:209]
	v_pk_fma_f32 v[210:211], v[8:9], v[206:207], v[210:211]
	v_add_f32_e32 v172, v208, v209
	v_add_f32_e32 v173, v210, v211
	s_add_i32 s53, s25, s78
	s_cmp_lt_i32 s53, 0xc000
	s_cselect_b32 s53, s53, s16
	s_add_i32 s54, s53, s78
	s_cmp_lt_i32 s54, 0xc000
	s_cselect_b32 s54, s54, s53
	s_add_i32 s56, s53, 0xffff8000
	s_cmp_lt_i32 s53, 0x8000
	s_cselect_b32 s56, s53, s56
	s_cselect_b32 s89, s37, s39
	s_cselect_b32 s88, s36, s38
	s_lshl_b32 s56, s56, 12
	s_add_u32 s88, s88, s56
	s_addc_u32 s89, s89, 0
	s_add_i32 s57, s54, 0xffff8000
	s_cmp_lt_i32 s54, 0x8000
	s_cselect_b32 s57, s54, s57
	s_cselect_b32 s91, s37, s39
	s_cselect_b32 s90, s36, s38
	s_lshl_b32 s57, s57, 12
	s_add_u32 s90, s90, s57
	s_addc_u32 s91, s91, 0
	global_load_dwordx4 v[26:29], v42, s[88:89]
	global_load_dwordx4 v[22:25], v42, s[88:89] offset:1024
	global_load_dwordx4 v[176:179], v42, s[88:89] offset:2048
	global_load_dwordx4 v[180:183], v42, s[88:89] offset:3072
	global_load_dwordx4 v[30:33], v42, s[90:91]
	global_load_dwordx4 v[18:21], v42, s[90:91] offset:1024
	global_load_dwordx4 v[184:187], v42, s[90:91] offset:2048
	global_load_dwordx4 v[188:191], v42, s[90:91] offset:3072
	v_cndmask_b32_e32 v4, v142, v158, vcc
	v_cndmask_b32_e32 v6, v144, v160, vcc
	v_cndmask_b32_e32 v7, v146, v162, vcc
	v_cndmask_b32_e32 v5, v158, v142, vcc
	s_waitcnt lgkmcnt(2)
	s_nop 0
	v_add_f32_dpp v4, v4, v5 quad_perm:[1,0,3,2] row_mask:0xf bank_mask:0xf
	v_cndmask_b32_e32 v5, v160, v144, vcc
	s_waitcnt lgkmcnt(1)
	s_nop 0
	v_add_f32_dpp v5, v6, v5 quad_perm:[1,0,3,2] row_mask:0xf bank_mask:0xf
	v_cndmask_b32_e32 v6, v162, v146, vcc
	s_waitcnt lgkmcnt(0)
	s_nop 0
	v_add_f32_dpp v6, v7, v6 quad_perm:[1,0,3,2] row_mask:0xf bank_mask:0xf
	v_cndmask_b32_e32 v7, v148, v164, vcc
	v_cndmask_b32_e32 v9, v150, v166, vcc
	v_cndmask_b32_e32 v10, v152, v168, vcc
	v_cndmask_b32_e32 v8, v164, v148, vcc
	s_waitcnt lgkmcnt(2)
	s_nop 0
	v_add_f32_dpp v7, v7, v8 quad_perm:[1,0,3,2] row_mask:0xf bank_mask:0xf
	v_cndmask_b32_e32 v8, v166, v150, vcc
	s_waitcnt lgkmcnt(1)
	s_nop 0
	v_add_f32_dpp v8, v9, v8 quad_perm:[1,0,3,2] row_mask:0xf bank_mask:0xf
	v_cndmask_b32_e32 v9, v168, v152, vcc
	v_cndmask_b32_e32 v13, v156, v172, vcc
	s_waitcnt lgkmcnt(0)
	v_add_f32_dpp v9, v10, v9 quad_perm:[1,0,3,2] row_mask:0xf bank_mask:0xf
	v_cndmask_b32_e32 v10, v154, v170, vcc
	v_cndmask_b32_e32 v2, v172, v156, vcc
	v_cndmask_b32_e32 v12, v170, v154, vcc
	s_waitcnt lgkmcnt(1)
	v_add_f32_dpp v2, v13, v2 quad_perm:[1,0,3,2] row_mask:0xf bank_mask:0xf
	v_cndmask_b32_e64 v14, v4, v8, s[0:1]
	s_waitcnt lgkmcnt(0)
	v_add_f32_dpp v10, v10, v12 quad_perm:[1,0,3,2] row_mask:0xf bank_mask:0xf
	v_cndmask_b32_e64 v4, v8, v4, s[0:1]
	v_cndmask_b32_e64 v8, v5, v9, s[0:1]
	v_cndmask_b32_e64 v12, v7, v2, s[0:1]
	v_cndmask_b32_e64 v5, v9, v5, s[0:1]
	v_cndmask_b32_e64 v9, v6, v10, s[0:1]
	v_cndmask_b32_e64 v2, v2, v7, s[0:1]
	s_waitcnt lgkmcnt(3)
	v_add_f32_dpp v5, v8, v5 quad_perm:[2,3,0,1] row_mask:0xf bank_mask:0xf
	s_waitcnt lgkmcnt(2)
	v_add_f32_dpp v2, v12, v2 quad_perm:[2,3,0,1] row_mask:0xf bank_mask:0xf
	v_cndmask_b32_e64 v8, v5, v2, s[8:9]
	v_cndmask_b32_e64 v6, v10, v6, s[0:1]
	s_waitcnt lgkmcnt(2)
	v_add_f32_dpp v4, v14, v4 quad_perm:[2,3,0,1] row_mask:0xf bank_mask:0xf
	s_waitcnt lgkmcnt(1)
	v_add_f32_dpp v6, v9, v6 quad_perm:[2,3,0,1] row_mask:0xf bank_mask:0xf
	v_cndmask_b32_e64 v7, v4, v6, s[8:9]
	v_cndmask_b32_e64 v4, v6, v4, s[8:9]
	v_cndmask_b32_e64 v2, v2, v5, s[8:9]
	v_cndmask_b32_e32 v6, v143, v159, vcc
	s_waitcnt lgkmcnt(1)
	v_add_f32_dpp v2, v8, v2 row_shl:4 row_mask:0xf bank_mask:0x5
	s_nop 1
	v_add_f32_dpp v2, v8, v2 row_shr:4 row_mask:0xf bank_mask:0xa
	v_cndmask_b32_e32 v8, v145, v161, vcc
	v_cndmask_b32_e32 v9, v147, v163, vcc
	s_waitcnt lgkmcnt(3)
	v_add_f32_dpp v4, v7, v4 row_shl:4 row_mask:0xf bank_mask:0x5
	s_nop 1
	v_add_f32_dpp v4, v7, v4 row_shr:4 row_mask:0xf bank_mask:0xa
	v_cndmask_b32_e32 v7, v159, v143, vcc
	s_waitcnt lgkmcnt(2)
	s_nop 0
	v_add_f32_dpp v6, v6, v7 quad_perm:[1,0,3,2] row_mask:0xf bank_mask:0xf
	v_cndmask_b32_e32 v7, v161, v145, vcc
	s_waitcnt lgkmcnt(1)
	s_nop 0
	v_add_f32_dpp v7, v8, v7 quad_perm:[1,0,3,2] row_mask:0xf bank_mask:0xf
	v_cndmask_b32_e32 v8, v163, v147, vcc
	s_waitcnt lgkmcnt(0)
	s_nop 0
	v_add_f32_dpp v8, v9, v8 quad_perm:[1,0,3,2] row_mask:0xf bank_mask:0xf
	v_cndmask_b32_e32 v9, v149, v165, vcc
	v_cndmask_b32_e32 v11, v151, v167, vcc
	v_cndmask_b32_e32 v12, v153, v169, vcc
	v_cndmask_b32_e32 v10, v165, v149, vcc
	s_waitcnt lgkmcnt(2)
	s_nop 0
	v_add_f32_dpp v9, v9, v10 quad_perm:[1,0,3,2] row_mask:0xf bank_mask:0xf
	v_cndmask_b32_e32 v10, v167, v151, vcc
	s_waitcnt lgkmcnt(1)
	s_nop 0
	v_add_f32_dpp v10, v11, v10 quad_perm:[1,0,3,2] row_mask:0xf bank_mask:0xf
	v_cndmask_b32_e32 v11, v169, v153, vcc
	s_waitcnt lgkmcnt(0)
	s_nop 0
	v_add_f32_dpp v11, v12, v11 quad_perm:[1,0,3,2] row_mask:0xf bank_mask:0xf
	v_cndmask_b32_e32 v12, v155, v171, vcc
	v_cndmask_b32_e32 v14, v157, v173, vcc
	v_cndmask_b32_e32 v13, v171, v155, vcc
	v_cndmask_b32_e32 v3, v173, v157, vcc
	v_cndmask_b32_e64 v15, v6, v10, s[0:1]
	s_waitcnt lgkmcnt(1)
	v_add_f32_dpp v12, v12, v13 quad_perm:[1,0,3,2] row_mask:0xf bank_mask:0xf
	s_waitcnt lgkmcnt(0)
	v_add_f32_dpp v3, v14, v3 quad_perm:[1,0,3,2] row_mask:0xf bank_mask:0xf
	v_cndmask_b32_e64 v6, v10, v6, s[0:1]
	v_cndmask_b32_e64 v10, v7, v11, s[0:1]
	v_cndmask_b32_e64 v7, v11, v7, s[0:1]
	v_cndmask_b32_e64 v11, v8, v12, s[0:1]
	v_cndmask_b32_e64 v13, v9, v3, s[0:1]
	v_cndmask_b32_e64 v8, v12, v8, s[0:1]
	v_cndmask_b32_e64 v3, v3, v9, s[0:1]
	s_waitcnt lgkmcnt(3)
	v_add_f32_dpp v6, v15, v6 quad_perm:[2,3,0,1] row_mask:0xf bank_mask:0xf
	s_waitcnt lgkmcnt(2)
	v_add_f32_dpp v7, v10, v7 quad_perm:[2,3,0,1] row_mask:0xf bank_mask:0xf
	s_waitcnt lgkmcnt(1)
	v_add_f32_dpp v8, v11, v8 quad_perm:[2,3,0,1] row_mask:0xf bank_mask:0xf
	s_waitcnt lgkmcnt(0)
	v_add_f32_dpp v3, v13, v3 quad_perm:[2,3,0,1] row_mask:0xf bank_mask:0xf
	v_cndmask_b32_e64 v9, v6, v8, s[8:9]
	v_cndmask_b32_e64 v10, v7, v3, s[8:9]
	v_cndmask_b32_e64 v6, v8, v6, s[8:9]
	v_cndmask_b32_e64 v3, v3, v7, s[8:9]
	v_cndmask_b32_e64 v5, v4, v2, s[4:5]
	s_waitcnt lgkmcnt(1)
	v_add_f32_dpp v6, v9, v6 row_shl:4 row_mask:0xf bank_mask:0x5
	s_nop 1
	v_add_f32_dpp v6, v9, v6 row_shr:4 row_mask:0xf bank_mask:0xa
	s_waitcnt lgkmcnt(0)
	v_add_f32_dpp v3, v10, v3 row_shl:4 row_mask:0xf bank_mask:0x5
	s_nop 1
	v_add_f32_dpp v3, v10, v3 row_shr:4 row_mask:0xf bank_mask:0xa
	v_cndmask_b32_e64 v7, v6, v3, s[4:5]
	v_cndmask_b32_e64 v2, v2, v4, s[4:5]
	v_cndmask_b32_e64 v3, v3, v6, s[4:5]
	s_waitcnt lgkmcnt(1)
	v_add_f32_dpp v2, v5, v2 row_shl:8 row_mask:0xf bank_mask:0x3
	s_nop 1
	v_add_f32_dpp v2, v5, v2 row_shr:8 row_mask:0xf bank_mask:0xc
	s_waitcnt lgkmcnt(0)
	v_add_f32_dpp v3, v7, v3 row_shl:8 row_mask:0xf bank_mask:0x3
	s_nop 1
	v_add_f32_dpp v3, v7, v3 row_shr:8 row_mask:0xf bank_mask:0xc
	ds_bpermute_b32 v4, v50, v2
	ds_bpermute_b32 v6, v50, v3
	s_waitcnt lgkmcnt(1)
	v_add_f32_e32 v4, v2, v4
	s_waitcnt lgkmcnt(0)
	v_add_f32_e32 v2, v3, v6
	ds_bpermute_b32 v5, v51, v4
	ds_bpermute_b32 v3, v51, v2
	s_and_saveexec_b64 s[18:19], s[6:7]
	s_cbranch_execz .LBB0_37
	s_waitcnt lgkmcnt(1)
	v_add_f32_e32 v4, v4, v5
	v_add_f32_e32 v4, v1, v4
	v_mul_f32_e64 v5, |v4|, s20
	v_exp_f32_e32 v5, v5
	s_waitcnt lgkmcnt(0)
	v_add_f32_e32 v2, v2, v3
	v_add_f32_e32 v6, v1, v2
	v_max_f32_e32 v4, 0, v4
	v_add_f32_e32 v7, 1.0, v5
	v_add_f32_e32 v2, -1.0, v7
	v_sub_f32_e32 v3, v2, v7
	v_add_f32_e32 v3, 1.0, v3
	v_sub_f32_e32 v2, v5, v2
	v_add_f32_e32 v8, v2, v3
	v_frexp_mant_f32_e32 v9, v7
	v_cvt_f64_f32_e32 v[2:3], v7
	v_frexp_exp_i32_f64_e32 v2, v[2:3]
	v_cmp_gt_f32_e64 s[10:11], s21, v9
	s_nop 1
	v_subbrev_co_u32_e64 v2, s[10:11], 0, v2, s[10:11]
	v_sub_u32_e32 v3, 0, v2
	v_ldexp_f32 v7, v7, v3
	v_ldexp_f32 v3, v8, v3
	v_add_f32_e32 v8, -1.0, v7
	v_add_f32_e32 v11, 1.0, v7
	v_add_f32_e32 v9, 1.0, v8
	v_add_f32_e32 v12, -1.0, v11
	v_sub_f32_e32 v9, v7, v9
	v_sub_f32_e32 v7, v7, v12
	v_add_f32_e32 v9, v3, v9
	v_add_f32_e32 v3, v3, v7
	v_add_f32_e32 v7, v11, v3
	v_rcp_f32_e32 v12, v7
	v_add_f32_e32 v10, v8, v9
	v_sub_f32_e32 v8, v10, v8
	v_sub_f32_e32 v8, v9, v8
	v_sub_f32_e32 v9, v7, v11
	v_sub_f32_e32 v3, v3, v9
	v_mul_f32_e32 v9, v10, v12
	v_mul_f32_e32 v11, v7, v9
	v_fma_f32 v13, v9, v7, -v11
	v_fmac_f32_e32 v13, v9, v3
	v_add_f32_e32 v14, v11, v13
	v_sub_f32_e32 v15, v10, v14
	v_sub_f32_e32 v10, v10, v15
	v_sub_f32_e32 v11, v14, v11
	v_sub_f32_e32 v10, v10, v14
	v_add_f32_e32 v8, v8, v10
	v_sub_f32_e32 v10, v11, v13
	v_add_f32_e32 v8, v10, v8
	v_add_f32_e32 v10, v15, v8
	v_mul_f32_e32 v11, v12, v10
	v_mul_f32_e32 v13, v7, v11
	v_fma_f32 v7, v11, v7, -v13
	v_fmac_f32_e32 v7, v11, v3
	v_sub_f32_e32 v3, v15, v10
	v_add_f32_e32 v3, v8, v3
	v_add_f32_e32 v8, v13, v7
	v_sub_f32_e32 v14, v10, v8
	v_sub_f32_e32 v10, v10, v14
	v_sub_f32_e32 v13, v8, v13
	v_sub_f32_e32 v8, v10, v8
	v_add_f32_e32 v3, v3, v8
	v_sub_f32_e32 v7, v13, v7
	v_cvt_f32_i32_e32 v2, v2
	v_add_f32_e32 v3, v7, v3
	v_add_f32_e32 v7, v9, v11
	v_add_f32_e32 v3, v14, v3
	v_sub_f32_e32 v8, v7, v9
	v_mul_f32_e32 v3, v12, v3
	v_sub_f32_e32 v8, v11, v8
	v_add_f32_e32 v3, v8, v3
	v_mul_f32_e32 v11, 0x3f317218, v2
	v_add_f32_e32 v8, v7, v3
	v_fma_f32 v12, v2, s22, -v11
	v_mul_f32_e32 v9, v8, v8
	v_fmac_f32_e32 v12, 0xb102e308, v2
	v_sub_f32_e32 v2, v8, v7
	v_fmamk_f32 v10, v9, 0x3e9b6dac, v52
	v_sub_f32_e32 v2, v3, v2
	v_add_f32_e32 v3, v11, v12
	v_fmaak_f32 v10, v9, v10, 0x3f2aaada
	v_sub_f32_e32 v7, v3, v11
	v_ldexp_f32 v11, v8, 1
	v_mul_f32_e32 v8, v8, v9
	v_mul_f32_e32 v8, v8, v10
	v_add_f32_e32 v9, v11, v8
	v_sub_f32_e32 v10, v9, v11
	v_ldexp_f32 v2, v2, 1
	v_sub_f32_e32 v8, v8, v10
	v_add_f32_e32 v2, v2, v8
	v_add_f32_e32 v8, v9, v2
	v_sub_f32_e32 v9, v8, v9
	v_sub_f32_e32 v2, v2, v9
	v_add_f32_e32 v9, v3, v8
	v_sub_f32_e32 v10, v9, v3
	v_sub_f32_e32 v11, v9, v10
	v_sub_f32_e32 v7, v12, v7
	v_sub_f32_e32 v3, v3, v11
	v_sub_f32_e32 v8, v8, v10
	v_add_f32_e32 v3, v8, v3
	v_add_f32_e32 v8, v7, v2
	v_sub_f32_e32 v10, v8, v7
	v_sub_f32_e32 v11, v8, v10
	v_sub_f32_e32 v7, v7, v11
	v_sub_f32_e32 v2, v2, v10
	v_add_f32_e32 v3, v8, v3
	v_add_f32_e32 v2, v2, v7
	v_add_f32_e32 v7, v9, v3
	v_sub_f32_e32 v8, v7, v9
	v_sub_f32_e32 v3, v3, v8
	v_add_f32_e32 v2, v2, v3
	v_add_f32_e32 v2, v7, v2
	v_cmp_neq_f32_e64 s[10:11], s23, v5
	s_nop 1
	v_cndmask_b32_e64 v2, v53, v2, s[10:11]
	v_cmp_ngt_f32_e64 s[10:11], -1.0, v5
	s_nop 1
	v_cndmask_b32_e64 v2, v54, v2, s[10:11]
	v_cmp_neq_f32_e64 s[10:11], -1.0, v5
	s_nop 1
	v_cndmask_b32_e64 v2, v55, v2, s[10:11]
	v_cmp_lt_f32_e64 s[10:11], |v5|, s24
	s_nop 1
	v_cndmask_b32_e64 v2, v2, v5, s[10:11]
	v_add_f32_e32 v4, v4, v2
	v_mul_f32_e64 v2, |v6|, s20
	v_exp_f32_e32 v5, v2
	s_lshl_b64 s[10:11], s[16:17], 6
	v_lshl_add_u64 v[2:3], v[38:39], 0, s[10:11]
	global_store_dword v[2:3], v4, off
	v_max_f32_e32 v4, 0, v6
	v_add_f32_e32 v6, 1.0, v5
	v_add_f32_e32 v2, -1.0, v6
	v_sub_f32_e32 v3, v2, v6
	v_add_f32_e32 v3, 1.0, v3
	v_sub_f32_e32 v2, v5, v2
	v_add_f32_e32 v7, v2, v3
	v_frexp_mant_f32_e32 v8, v6
	v_cvt_f64_f32_e32 v[2:3], v6
	v_frexp_exp_i32_f64_e32 v2, v[2:3]
	v_cmp_gt_f32_e64 s[10:11], s21, v8
	s_nop 1
	v_subbrev_co_u32_e64 v2, s[10:11], 0, v2, s[10:11]
	v_sub_u32_e32 v3, 0, v2
	v_ldexp_f32 v6, v6, v3
	v_ldexp_f32 v3, v7, v3
	v_add_f32_e32 v7, -1.0, v6
	v_add_f32_e32 v10, 1.0, v6
	v_add_f32_e32 v8, 1.0, v7
	v_add_f32_e32 v11, -1.0, v10
	v_sub_f32_e32 v8, v6, v8
	v_sub_f32_e32 v6, v6, v11
	v_add_f32_e32 v8, v3, v8
	v_add_f32_e32 v3, v3, v6
	v_add_f32_e32 v6, v10, v3
	v_rcp_f32_e32 v11, v6
	v_add_f32_e32 v9, v7, v8
	v_sub_f32_e32 v7, v9, v7
	v_sub_f32_e32 v7, v8, v7
	v_sub_f32_e32 v8, v6, v10
	v_sub_f32_e32 v3, v3, v8
	v_mul_f32_e32 v8, v9, v11
	v_mul_f32_e32 v10, v6, v8
	v_fma_f32 v12, v8, v6, -v10
	v_fmac_f32_e32 v12, v8, v3
	v_add_f32_e32 v13, v10, v12
	v_sub_f32_e32 v14, v9, v13
	v_sub_f32_e32 v9, v9, v14
	v_sub_f32_e32 v10, v13, v10
	v_sub_f32_e32 v9, v9, v13
	v_add_f32_e32 v7, v7, v9
	v_sub_f32_e32 v9, v10, v12
	v_add_f32_e32 v7, v9, v7
	v_add_f32_e32 v9, v14, v7
	v_mul_f32_e32 v10, v11, v9
	v_mul_f32_e32 v12, v6, v10
	v_fma_f32 v6, v10, v6, -v12
	v_fmac_f32_e32 v6, v10, v3
	v_sub_f32_e32 v3, v14, v9
	v_add_f32_e32 v3, v7, v3
	v_add_f32_e32 v7, v12, v6
	v_sub_f32_e32 v13, v9, v7
	v_sub_f32_e32 v9, v9, v13
	v_sub_f32_e32 v12, v7, v12
	v_sub_f32_e32 v7, v9, v7
	v_add_f32_e32 v3, v3, v7
	v_sub_f32_e32 v6, v12, v6
	v_cvt_f32_i32_e32 v2, v2
	v_add_f32_e32 v3, v6, v3
	v_add_f32_e32 v6, v8, v10
	v_add_f32_e32 v3, v13, v3
	v_sub_f32_e32 v7, v6, v8
	v_mul_f32_e32 v3, v11, v3
	v_sub_f32_e32 v7, v10, v7
	v_add_f32_e32 v3, v7, v3
	v_mul_f32_e32 v10, 0x3f317218, v2
	v_add_f32_e32 v7, v6, v3
	v_fma_f32 v11, v2, s22, -v10
	v_mul_f32_e32 v8, v7, v7
	v_fmac_f32_e32 v11, 0xb102e308, v2
	v_sub_f32_e32 v2, v7, v6
	v_fmamk_f32 v9, v8, 0x3e9b6dac, v52
	v_sub_f32_e32 v2, v3, v2
	v_add_f32_e32 v3, v10, v11
	v_fmaak_f32 v9, v8, v9, 0x3f2aaada
	v_sub_f32_e32 v6, v3, v10
	v_ldexp_f32 v10, v7, 1
	v_mul_f32_e32 v7, v7, v8
	v_mul_f32_e32 v7, v7, v9
	v_add_f32_e32 v8, v10, v7
	v_sub_f32_e32 v9, v8, v10
	v_ldexp_f32 v2, v2, 1
	v_sub_f32_e32 v7, v7, v9
	v_add_f32_e32 v2, v2, v7
	v_add_f32_e32 v7, v8, v2
	v_sub_f32_e32 v8, v7, v8
	v_sub_f32_e32 v2, v2, v8
	v_add_f32_e32 v8, v3, v7
	v_sub_f32_e32 v9, v8, v3
	v_sub_f32_e32 v10, v8, v9
	v_sub_f32_e32 v6, v11, v6
	v_sub_f32_e32 v3, v3, v10
	v_sub_f32_e32 v7, v7, v9
	v_add_f32_e32 v3, v7, v3
	v_add_f32_e32 v7, v6, v2
	v_sub_f32_e32 v9, v7, v6
	v_sub_f32_e32 v10, v7, v9
	v_sub_f32_e32 v6, v6, v10
	v_sub_f32_e32 v2, v2, v9
	v_add_f32_e32 v3, v7, v3
	v_add_f32_e32 v2, v2, v6
	v_add_f32_e32 v6, v8, v3
	v_sub_f32_e32 v7, v6, v8
	v_sub_f32_e32 v3, v3, v7
	v_add_f32_e32 v2, v2, v3
	v_add_f32_e32 v2, v6, v2
	v_cmp_neq_f32_e64 s[10:11], s23, v5
	s_nop 1
	v_cndmask_b32_e64 v2, v53, v2, s[10:11]
	v_cmp_ngt_f32_e64 s[10:11], -1.0, v5
	s_nop 1
	v_cndmask_b32_e64 v2, v54, v2, s[10:11]
	v_cmp_neq_f32_e64 s[10:11], -1.0, v5
	s_nop 1
	v_cndmask_b32_e64 v2, v55, v2, s[10:11]
	v_cmp_lt_f32_e64 s[10:11], |v5|, s24
	s_nop 1
	v_cndmask_b32_e64 v2, v2, v5, s[10:11]
	s_lshl_b64 s[10:11], s[14:15], 6
	v_add_f32_e32 v4, v4, v2
	v_lshl_add_u64 v[2:3], v[38:39], 0, s[10:11]
	global_store_dword v[2:3], v4, off
	s_branch .LBB0_37
